# adds pipelined residual epilogues (WO, FF2): base loads run 5 groups ahead of the adds and stores
# baseline (speedup 1.0000x reference)
.LBB0_958:
	v_and_b32_e32 v205, 63, v206
	v_lshrrev_b32_e32 v214, 6, v206
	v_and_b32_e32 v215, 15, v205
	v_readfirstlane_b32 s13, v214
	v_lshrrev_b32_e32 v178, 4, v205
	v_xor_b32_e32 v240, 16, v205
	v_xor_b32_e32 v241, 32, v205
	v_lshlrev_b32_e32 v240, 2, v240
	v_lshlrev_b32_e32 v241, 2, v241
	s_and_b32 s20, s13, 3
	s_mov_b32 s22, s20
	s_lshl_b32 s20, s20, 5
	s_lshl_b32 s21, s33, 8
	s_add_i32 s20, s20, s21
	v_lshl_add_u32 v179, v178, 3, s20
	s_lshl_b32 s21, s33, 2
	s_add_i32 s22, s22, s21
	s_lshl_b32 s22, s22, 2
	s_lshr_b32 s20, s13, 2
	s_lshl_b32 s20, s20, 6
	s_lshl_b32 s21, s38, 8
	s_add_i32 s20, s20, s21
	v_add_u32_e32 v174, s20, v215
	v_lshlrev_b32_e32 v183, 12, v174
	v_lshl_add_u32 v183, v179, 2, v183
	v_lshrrev_b32_e32 v184, 1, v183
	v_lshl_add_u32 v242, v174, 6, s22
	v_mov_b32_e32 v185, v183
	v_mov_b32_e32 v186, v184
	global_load_dwordx4 v[188:191], v185, s[2:3]
	global_load_dwordx4 v[192:195], v185, s[2:3] offset:16
	global_load_dwordx4 v[196:199], v185, s[2:3] offset:512
	global_load_dwordx4 v[200:203], v185, s[2:3] offset:528
	v_add_u32_e32 v187, 0x10000, v183
	v_add_u32_e32 v204, 0x8000, v184
	global_load_dwordx4 v[216:219], v187, s[2:3]
	global_load_dwordx4 v[220:223], v187, s[2:3] offset:16
	global_load_dwordx4 v[224:227], v187, s[2:3] offset:512
	global_load_dwordx4 v[228:231], v187, s[2:3] offset:528
	v_add_u32_e32 v243, 0x20000, v183
	v_add_u32_e32 v214, 0x10000, v184
	global_load_dwordx4 v[232:235], v243, s[2:3]
	global_load_dwordx4 v[236:239], v243, s[2:3] offset:16
	s_waitcnt vmcnt(8)
	v_pk_add_f32 v[132:133], v[132:133], v[188:189]
	v_pk_add_f32 v[134:135], v[134:135], v[190:191]
	v_pk_add_f32 v[128:129], v[128:129], v[192:193]
	v_pk_add_f32 v[130:131], v[130:131], v[194:195]
	global_load_dwordx4 v[188:191], v243, s[2:3] offset:512
	global_load_dwordx4 v[192:195], v243, s[2:3] offset:528
	global_store_dwordx4 v185, v[132:135], s[4:5]
	global_store_dwordx4 v185, v[128:131], s[4:5] offset:16
	v_cvt_pk_bf16_f32 v174, v132, v133
	v_cvt_pk_bf16_f32 v175, v134, v135
	v_cvt_pk_bf16_f32 v176, v128, v129
	v_cvt_pk_bf16_f32 v177, v130, v131
	global_store_dwordx4 v186, v[174:177], s[6:7]
	v_mul_f32_e32 v178, v133, v133
	v_fmac_f32_e32 v178, v132, v132
	v_mul_f32_e32 v179, v135, v135
	v_fmac_f32_e32 v179, v134, v134
	v_add_f32_e32 v178, v178, v179
	v_mul_f32_e32 v179, v129, v129
	v_fmac_f32_e32 v179, v128, v128
	v_add_f32_e32 v178, v178, v179
	v_mul_f32_e32 v179, v131, v131
	v_fmac_f32_e32 v179, v130, v130
	v_add_f32_e32 v146, v179, v178
	s_waitcnt vmcnt(11)
	v_pk_add_f32 v[124:125], v[124:125], v[196:197]
	v_pk_add_f32 v[126:127], v[126:127], v[198:199]
	v_pk_add_f32 v[120:121], v[120:121], v[200:201]
	v_pk_add_f32 v[122:123], v[122:123], v[202:203]
	v_add_u32_e32 v215, 0x30000, v183
	v_add_u32_e32 v205, 0x18000, v184
	global_load_dwordx4 v[196:199], v215, s[2:3]
	global_load_dwordx4 v[200:203], v215, s[2:3] offset:16
	global_store_dwordx4 v185, v[124:127], s[4:5] offset:512
	global_store_dwordx4 v185, v[120:123], s[4:5] offset:528
	v_cvt_pk_bf16_f32 v244, v124, v125
	v_cvt_pk_bf16_f32 v245, v126, v127
	v_cvt_pk_bf16_f32 v246, v120, v121
	v_cvt_pk_bf16_f32 v247, v122, v123
	global_store_dwordx4 v186, v[244:247], s[6:7] offset:256
	v_mul_f32_e32 v178, v125, v125
	v_fmac_f32_e32 v178, v124, v124
	v_mul_f32_e32 v179, v127, v127
	v_fmac_f32_e32 v179, v126, v126
	v_add_f32_e32 v178, v178, v179
	v_mul_f32_e32 v179, v121, v121
	v_fmac_f32_e32 v179, v120, v120
	v_add_f32_e32 v178, v178, v179
	v_mul_f32_e32 v179, v123, v123
	v_fmac_f32_e32 v179, v122, v122
	v_add_f32_e32 v178, v179, v178
	v_add_f32_e32 v146, v146, v178
	s_waitcnt vmcnt(14)
	v_pk_add_f32 v[116:117], v[116:117], v[216:217]
	v_pk_add_f32 v[118:119], v[118:119], v[218:219]
	v_pk_add_f32 v[112:113], v[112:113], v[220:221]
	v_pk_add_f32 v[114:115], v[114:115], v[222:223]
	global_load_dwordx4 v[216:219], v215, s[2:3] offset:512
	global_load_dwordx4 v[220:223], v215, s[2:3] offset:528
	global_store_dwordx4 v187, v[116:119], s[4:5]
	global_store_dwordx4 v187, v[112:115], s[4:5] offset:16
	v_cvt_pk_bf16_f32 v174, v116, v117
	v_cvt_pk_bf16_f32 v175, v118, v119
	v_cvt_pk_bf16_f32 v176, v112, v113
	v_cvt_pk_bf16_f32 v177, v114, v115
	global_store_dwordx4 v204, v[174:177], s[6:7]
	v_mul_f32_e32 v178, v117, v117
	v_fmac_f32_e32 v178, v116, v116
	v_mul_f32_e32 v179, v119, v119
	v_fmac_f32_e32 v179, v118, v118
	v_add_f32_e32 v178, v178, v179
	v_mul_f32_e32 v179, v113, v113
	v_fmac_f32_e32 v179, v112, v112
	v_add_f32_e32 v178, v178, v179
	v_mul_f32_e32 v179, v115, v115
	v_fmac_f32_e32 v179, v114, v114
	v_add_f32_e32 v147, v179, v178
	s_waitcnt vmcnt(17)
	v_pk_add_f32 v[108:109], v[108:109], v[224:225]
	v_pk_add_f32 v[110:111], v[110:111], v[226:227]
	v_pk_add_f32 v[104:105], v[104:105], v[228:229]
	v_pk_add_f32 v[106:107], v[106:107], v[230:231]
	v_add_u32_e32 v185, 0x80000, v183
	v_add_u32_e32 v186, 0x40000, v184
	global_load_dwordx4 v[224:227], v185, s[2:3]
	global_load_dwordx4 v[228:231], v185, s[2:3] offset:16
	global_store_dwordx4 v187, v[108:111], s[4:5] offset:512
	global_store_dwordx4 v187, v[104:107], s[4:5] offset:528
	v_cvt_pk_bf16_f32 v244, v108, v109
	v_cvt_pk_bf16_f32 v245, v110, v111
	v_cvt_pk_bf16_f32 v246, v104, v105
	v_cvt_pk_bf16_f32 v247, v106, v107
	global_store_dwordx4 v204, v[244:247], s[6:7] offset:256
	v_mul_f32_e32 v178, v109, v109
	v_fmac_f32_e32 v178, v108, v108
	v_mul_f32_e32 v179, v111, v111
	v_fmac_f32_e32 v179, v110, v110
	v_add_f32_e32 v178, v178, v179
	v_mul_f32_e32 v179, v105, v105
	v_fmac_f32_e32 v179, v104, v104
	v_add_f32_e32 v178, v178, v179
	v_mul_f32_e32 v179, v107, v107
	v_fmac_f32_e32 v179, v106, v106
	v_add_f32_e32 v178, v179, v178
	v_add_f32_e32 v147, v147, v178
	s_waitcnt vmcnt(20)
	v_pk_add_f32 v[100:101], v[100:101], v[232:233]
	v_pk_add_f32 v[102:103], v[102:103], v[234:235]
	v_pk_add_f32 v[96:97], v[96:97], v[236:237]
	v_pk_add_f32 v[98:99], v[98:99], v[238:239]
	global_load_dwordx4 v[232:235], v185, s[2:3] offset:512
	global_load_dwordx4 v[236:239], v185, s[2:3] offset:528
	global_store_dwordx4 v243, v[100:103], s[4:5]
	global_store_dwordx4 v243, v[96:99], s[4:5] offset:16
	v_cvt_pk_bf16_f32 v174, v100, v101
	v_cvt_pk_bf16_f32 v175, v102, v103
	v_cvt_pk_bf16_f32 v176, v96, v97
	v_cvt_pk_bf16_f32 v177, v98, v99
	global_store_dwordx4 v214, v[174:177], s[6:7]
	v_mul_f32_e32 v178, v101, v101
	v_fmac_f32_e32 v178, v100, v100
	v_mul_f32_e32 v179, v103, v103
	v_fmac_f32_e32 v179, v102, v102
	v_add_f32_e32 v178, v178, v179
	v_mul_f32_e32 v179, v97, v97
	v_fmac_f32_e32 v179, v96, v96
	v_add_f32_e32 v178, v178, v179
	v_mul_f32_e32 v179, v99, v99
	v_fmac_f32_e32 v179, v98, v98
	v_add_f32_e32 v148, v179, v178
	s_waitcnt vmcnt(23)
	v_pk_add_f32 v[92:93], v[92:93], v[188:189]
	v_pk_add_f32 v[94:95], v[94:95], v[190:191]
	v_pk_add_f32 v[88:89], v[88:89], v[192:193]
	v_pk_add_f32 v[90:91], v[90:91], v[194:195]
	v_add_u32_e32 v187, 0x90000, v183
	v_add_u32_e32 v204, 0x48000, v184
	global_load_dwordx4 v[188:191], v187, s[2:3]
	global_load_dwordx4 v[192:195], v187, s[2:3] offset:16
	global_store_dwordx4 v243, v[92:95], s[4:5] offset:512
	global_store_dwordx4 v243, v[88:91], s[4:5] offset:528
	v_cvt_pk_bf16_f32 v244, v92, v93
	v_cvt_pk_bf16_f32 v245, v94, v95
	v_cvt_pk_bf16_f32 v246, v88, v89
	v_cvt_pk_bf16_f32 v247, v90, v91
	global_store_dwordx4 v214, v[244:247], s[6:7] offset:256
	v_mul_f32_e32 v178, v93, v93
	v_fmac_f32_e32 v178, v92, v92
	v_mul_f32_e32 v179, v95, v95
	v_fmac_f32_e32 v179, v94, v94
	v_add_f32_e32 v178, v178, v179
	v_mul_f32_e32 v179, v89, v89
	v_fmac_f32_e32 v179, v88, v88
	v_add_f32_e32 v178, v178, v179
	v_mul_f32_e32 v179, v91, v91
	v_fmac_f32_e32 v179, v90, v90
	v_add_f32_e32 v178, v179, v178
	v_add_f32_e32 v148, v148, v178
	s_waitcnt vmcnt(23)
	v_pk_add_f32 v[84:85], v[84:85], v[196:197]
	v_pk_add_f32 v[86:87], v[86:87], v[198:199]
	v_pk_add_f32 v[80:81], v[80:81], v[200:201]
	v_pk_add_f32 v[82:83], v[82:83], v[202:203]
	global_load_dwordx4 v[196:199], v187, s[2:3] offset:512
	global_load_dwordx4 v[200:203], v187, s[2:3] offset:528
	global_store_dwordx4 v215, v[84:87], s[4:5]
	global_store_dwordx4 v215, v[80:83], s[4:5] offset:16
	v_cvt_pk_bf16_f32 v174, v84, v85
	v_cvt_pk_bf16_f32 v175, v86, v87
	v_cvt_pk_bf16_f32 v176, v80, v81
	v_cvt_pk_bf16_f32 v177, v82, v83
	global_store_dwordx4 v205, v[174:177], s[6:7]
	v_mul_f32_e32 v178, v85, v85
	v_fmac_f32_e32 v178, v84, v84
	v_mul_f32_e32 v179, v87, v87
	v_fmac_f32_e32 v179, v86, v86
	v_add_f32_e32 v178, v178, v179
	v_mul_f32_e32 v179, v81, v81
	v_fmac_f32_e32 v179, v80, v80
	v_add_f32_e32 v178, v178, v179
	v_mul_f32_e32 v179, v83, v83
	v_fmac_f32_e32 v179, v82, v82
	v_add_f32_e32 v149, v179, v178
	s_waitcnt vmcnt(23)
	v_pk_add_f32 v[76:77], v[76:77], v[216:217]
	v_pk_add_f32 v[78:79], v[78:79], v[218:219]
	v_pk_add_f32 v[72:73], v[72:73], v[220:221]
	v_pk_add_f32 v[74:75], v[74:75], v[222:223]
	v_add_u32_e32 v243, 0xa0000, v183
	v_add_u32_e32 v214, 0x50000, v184
	global_load_dwordx4 v[216:219], v243, s[2:3]
	global_load_dwordx4 v[220:223], v243, s[2:3] offset:16
	global_store_dwordx4 v215, v[76:79], s[4:5] offset:512
	global_store_dwordx4 v215, v[72:75], s[4:5] offset:528
	v_cvt_pk_bf16_f32 v244, v76, v77
	v_cvt_pk_bf16_f32 v245, v78, v79
	v_cvt_pk_bf16_f32 v246, v72, v73
	v_cvt_pk_bf16_f32 v247, v74, v75
	global_store_dwordx4 v205, v[244:247], s[6:7] offset:256
	v_mul_f32_e32 v178, v77, v77
	v_fmac_f32_e32 v178, v76, v76
	v_mul_f32_e32 v179, v79, v79
	v_fmac_f32_e32 v179, v78, v78
	v_add_f32_e32 v178, v178, v179
	v_mul_f32_e32 v179, v73, v73
	v_fmac_f32_e32 v179, v72, v72
	v_add_f32_e32 v178, v178, v179
	v_mul_f32_e32 v179, v75, v75
	v_fmac_f32_e32 v179, v74, v74
	v_add_f32_e32 v178, v179, v178
	v_add_f32_e32 v149, v149, v178
	s_waitcnt vmcnt(23)
	v_pk_add_f32 v[68:69], v[68:69], v[224:225]
	v_pk_add_f32 v[70:71], v[70:71], v[226:227]
	v_pk_add_f32 v[64:65], v[64:65], v[228:229]
	v_pk_add_f32 v[66:67], v[66:67], v[230:231]
	global_load_dwordx4 v[224:227], v243, s[2:3] offset:512
	global_load_dwordx4 v[228:231], v243, s[2:3] offset:528
	global_store_dwordx4 v185, v[68:71], s[4:5]
	global_store_dwordx4 v185, v[64:67], s[4:5] offset:16
	v_cvt_pk_bf16_f32 v174, v68, v69
	v_cvt_pk_bf16_f32 v175, v70, v71
	v_cvt_pk_bf16_f32 v176, v64, v65
	v_cvt_pk_bf16_f32 v177, v66, v67
	global_store_dwordx4 v186, v[174:177], s[6:7]
	v_mul_f32_e32 v178, v69, v69
	v_fmac_f32_e32 v178, v68, v68
	v_mul_f32_e32 v179, v71, v71
	v_fmac_f32_e32 v179, v70, v70
	v_add_f32_e32 v178, v178, v179
	v_mul_f32_e32 v179, v65, v65
	v_fmac_f32_e32 v179, v64, v64
	v_add_f32_e32 v178, v178, v179
	v_mul_f32_e32 v179, v67, v67
	v_fmac_f32_e32 v179, v66, v66
	v_add_f32_e32 v160, v179, v178
	s_waitcnt vmcnt(23)
	v_pk_add_f32 v[60:61], v[60:61], v[232:233]
	v_pk_add_f32 v[62:63], v[62:63], v[234:235]
	v_pk_add_f32 v[56:57], v[56:57], v[236:237]
	v_pk_add_f32 v[58:59], v[58:59], v[238:239]
	v_add_u32_e32 v215, 0xb0000, v183
	v_add_u32_e32 v205, 0x58000, v184
	global_load_dwordx4 v[232:235], v215, s[2:3]
	global_load_dwordx4 v[236:239], v215, s[2:3] offset:16
	global_store_dwordx4 v185, v[60:63], s[4:5] offset:512
	global_store_dwordx4 v185, v[56:59], s[4:5] offset:528
	v_cvt_pk_bf16_f32 v244, v60, v61
	v_cvt_pk_bf16_f32 v245, v62, v63
	v_cvt_pk_bf16_f32 v246, v56, v57
	v_cvt_pk_bf16_f32 v247, v58, v59
	global_store_dwordx4 v186, v[244:247], s[6:7] offset:256
	v_mul_f32_e32 v178, v61, v61
	v_fmac_f32_e32 v178, v60, v60
	v_mul_f32_e32 v179, v63, v63
	v_fmac_f32_e32 v179, v62, v62
	v_add_f32_e32 v178, v178, v179
	v_mul_f32_e32 v179, v57, v57
	v_fmac_f32_e32 v179, v56, v56
	v_add_f32_e32 v178, v178, v179
	v_mul_f32_e32 v179, v59, v59
	v_fmac_f32_e32 v179, v58, v58
	v_add_f32_e32 v178, v179, v178
	v_add_f32_e32 v160, v160, v178
	s_waitcnt vmcnt(23)
	v_pk_add_f32 v[52:53], v[52:53], v[188:189]
	v_pk_add_f32 v[54:55], v[54:55], v[190:191]
	v_pk_add_f32 v[48:49], v[48:49], v[192:193]
	v_pk_add_f32 v[50:51], v[50:51], v[194:195]
	global_load_dwordx4 v[188:191], v215, s[2:3] offset:512
	global_load_dwordx4 v[192:195], v215, s[2:3] offset:528
	global_store_dwordx4 v187, v[52:55], s[4:5]
	global_store_dwordx4 v187, v[48:51], s[4:5] offset:16
	v_cvt_pk_bf16_f32 v174, v52, v53
	v_cvt_pk_bf16_f32 v175, v54, v55
	v_cvt_pk_bf16_f32 v176, v48, v49
	v_cvt_pk_bf16_f32 v177, v50, v51
	global_store_dwordx4 v204, v[174:177], s[6:7]
	v_mul_f32_e32 v178, v53, v53
	v_fmac_f32_e32 v178, v52, v52
	v_mul_f32_e32 v179, v55, v55
	v_fmac_f32_e32 v179, v54, v54
	v_add_f32_e32 v178, v178, v179
	v_mul_f32_e32 v179, v49, v49
	v_fmac_f32_e32 v179, v48, v48
	v_add_f32_e32 v178, v178, v179
	v_mul_f32_e32 v179, v51, v51
	v_fmac_f32_e32 v179, v50, v50
	v_add_f32_e32 v161, v179, v178
	s_waitcnt vmcnt(23)
	v_pk_add_f32 v[44:45], v[44:45], v[196:197]
	v_pk_add_f32 v[46:47], v[46:47], v[198:199]
	v_pk_add_f32 v[40:41], v[40:41], v[200:201]
	v_pk_add_f32 v[42:43], v[42:43], v[202:203]
	global_store_dwordx4 v187, v[44:47], s[4:5] offset:512
	global_store_dwordx4 v187, v[40:43], s[4:5] offset:528
	v_cvt_pk_bf16_f32 v244, v44, v45
	v_cvt_pk_bf16_f32 v245, v46, v47
	v_cvt_pk_bf16_f32 v246, v40, v41
	v_cvt_pk_bf16_f32 v247, v42, v43
	global_store_dwordx4 v204, v[244:247], s[6:7] offset:256
	v_mul_f32_e32 v178, v45, v45
	v_fmac_f32_e32 v178, v44, v44
	v_mul_f32_e32 v179, v47, v47
	v_fmac_f32_e32 v179, v46, v46
	v_add_f32_e32 v178, v178, v179
	v_mul_f32_e32 v179, v41, v41
	v_fmac_f32_e32 v179, v40, v40
	v_add_f32_e32 v178, v178, v179
	v_mul_f32_e32 v179, v43, v43
	v_fmac_f32_e32 v179, v42, v42
	v_add_f32_e32 v178, v179, v178
	v_add_f32_e32 v161, v161, v178
	s_waitcnt vmcnt(21)
	v_pk_add_f32 v[36:37], v[36:37], v[216:217]
	v_pk_add_f32 v[38:39], v[38:39], v[218:219]
	v_pk_add_f32 v[32:33], v[32:33], v[220:221]
	v_pk_add_f32 v[34:35], v[34:35], v[222:223]
	global_store_dwordx4 v243, v[36:39], s[4:5]
	global_store_dwordx4 v243, v[32:35], s[4:5] offset:16
	v_cvt_pk_bf16_f32 v174, v36, v37
	v_cvt_pk_bf16_f32 v175, v38, v39
	v_cvt_pk_bf16_f32 v176, v32, v33
	v_cvt_pk_bf16_f32 v177, v34, v35
	global_store_dwordx4 v214, v[174:177], s[6:7]
	v_mul_f32_e32 v178, v37, v37
	v_fmac_f32_e32 v178, v36, v36
	v_mul_f32_e32 v179, v39, v39
	v_fmac_f32_e32 v179, v38, v38
	v_add_f32_e32 v178, v178, v179
	v_mul_f32_e32 v179, v33, v33
	v_fmac_f32_e32 v179, v32, v32
	v_add_f32_e32 v178, v178, v179
	v_mul_f32_e32 v179, v35, v35
	v_fmac_f32_e32 v179, v34, v34
	v_add_f32_e32 v162, v179, v178
	s_waitcnt vmcnt(19)
	v_pk_add_f32 v[28:29], v[28:29], v[224:225]
	v_pk_add_f32 v[30:31], v[30:31], v[226:227]
	v_pk_add_f32 v[24:25], v[24:25], v[228:229]
	v_pk_add_f32 v[26:27], v[26:27], v[230:231]
	global_store_dwordx4 v243, v[28:31], s[4:5] offset:512
	global_store_dwordx4 v243, v[24:27], s[4:5] offset:528
	v_cvt_pk_bf16_f32 v244, v28, v29
	v_cvt_pk_bf16_f32 v245, v30, v31
	v_cvt_pk_bf16_f32 v246, v24, v25
	v_cvt_pk_bf16_f32 v247, v26, v27
	global_store_dwordx4 v214, v[244:247], s[6:7] offset:256
	v_mul_f32_e32 v178, v29, v29
	v_fmac_f32_e32 v178, v28, v28
	v_mul_f32_e32 v179, v31, v31
	v_fmac_f32_e32 v179, v30, v30
	v_add_f32_e32 v178, v178, v179
	v_mul_f32_e32 v179, v25, v25
	v_fmac_f32_e32 v179, v24, v24
	v_add_f32_e32 v178, v178, v179
	v_mul_f32_e32 v179, v27, v27
	v_fmac_f32_e32 v179, v26, v26
	v_add_f32_e32 v178, v179, v178
	v_add_f32_e32 v162, v162, v178
	s_waitcnt vmcnt(17)
	v_pk_add_f32 v[20:21], v[20:21], v[232:233]
	v_pk_add_f32 v[22:23], v[22:23], v[234:235]
	v_pk_add_f32 v[16:17], v[16:17], v[236:237]
	v_pk_add_f32 v[18:19], v[18:19], v[238:239]
	global_store_dwordx4 v215, v[20:23], s[4:5]
	global_store_dwordx4 v215, v[16:19], s[4:5] offset:16
	v_cvt_pk_bf16_f32 v174, v20, v21
	v_cvt_pk_bf16_f32 v175, v22, v23
	v_cvt_pk_bf16_f32 v176, v16, v17
	v_cvt_pk_bf16_f32 v177, v18, v19
	global_store_dwordx4 v205, v[174:177], s[6:7]
	v_mul_f32_e32 v178, v21, v21
	v_fmac_f32_e32 v178, v20, v20
	v_mul_f32_e32 v179, v23, v23
	v_fmac_f32_e32 v179, v22, v22
	v_add_f32_e32 v178, v178, v179
	v_mul_f32_e32 v179, v17, v17
	v_fmac_f32_e32 v179, v16, v16
	v_add_f32_e32 v178, v178, v179
	v_mul_f32_e32 v179, v19, v19
	v_fmac_f32_e32 v179, v18, v18
	v_add_f32_e32 v163, v179, v178
	s_waitcnt vmcnt(15)
	v_pk_add_f32 v[12:13], v[12:13], v[188:189]
	v_pk_add_f32 v[14:15], v[14:15], v[190:191]
	v_pk_add_f32 v[8:9], v[8:9], v[192:193]
	v_pk_add_f32 v[10:11], v[10:11], v[194:195]
	global_store_dwordx4 v215, v[12:15], s[4:5] offset:512
	global_store_dwordx4 v215, v[8:11], s[4:5] offset:528
	v_cvt_pk_bf16_f32 v244, v12, v13
	v_cvt_pk_bf16_f32 v245, v14, v15
	v_cvt_pk_bf16_f32 v246, v8, v9
	v_cvt_pk_bf16_f32 v247, v10, v11
	global_store_dwordx4 v205, v[244:247], s[6:7] offset:256
	v_mul_f32_e32 v178, v13, v13
	v_fmac_f32_e32 v178, v12, v12
	v_mul_f32_e32 v179, v15, v15
	v_fmac_f32_e32 v179, v14, v14
	v_add_f32_e32 v178, v178, v179
	v_mul_f32_e32 v179, v9, v9
	v_fmac_f32_e32 v179, v8, v8
	v_add_f32_e32 v178, v178, v179
	v_mul_f32_e32 v179, v11, v11
	v_fmac_f32_e32 v179, v10, v10
	v_add_f32_e32 v178, v179, v178
	v_add_f32_e32 v163, v163, v178
	ds_bpermute_b32 v188, v240, v146
	ds_bpermute_b32 v192, v240, v147
	ds_bpermute_b32 v196, v240, v148
	ds_bpermute_b32 v200, v240, v149
	ds_bpermute_b32 v216, v240, v160
	ds_bpermute_b32 v220, v240, v161
	ds_bpermute_b32 v224, v240, v162
	ds_bpermute_b32 v228, v240, v163
	s_waitcnt lgkmcnt(7)
	v_add_f32_e32 v146, v146, v188
	s_waitcnt lgkmcnt(6)
	v_add_f32_e32 v147, v147, v192
	s_waitcnt lgkmcnt(5)
	v_add_f32_e32 v148, v148, v196
	s_waitcnt lgkmcnt(4)
	v_add_f32_e32 v149, v149, v200
	s_waitcnt lgkmcnt(3)
	v_add_f32_e32 v160, v160, v216
	s_waitcnt lgkmcnt(2)
	v_add_f32_e32 v161, v161, v220
	s_waitcnt lgkmcnt(1)
	v_add_f32_e32 v162, v162, v224
	s_waitcnt lgkmcnt(0)
	v_add_f32_e32 v163, v163, v228
	ds_bpermute_b32 v188, v241, v146
	ds_bpermute_b32 v192, v241, v147
	ds_bpermute_b32 v196, v241, v148
	ds_bpermute_b32 v200, v241, v149
	ds_bpermute_b32 v216, v241, v160
	ds_bpermute_b32 v220, v241, v161
	ds_bpermute_b32 v224, v241, v162
	ds_bpermute_b32 v228, v241, v163
	s_waitcnt lgkmcnt(7)
	v_add_f32_e32 v146, v146, v188
	s_waitcnt lgkmcnt(6)
	v_add_f32_e32 v147, v147, v192
	s_waitcnt lgkmcnt(5)
	v_add_f32_e32 v148, v148, v196
	s_waitcnt lgkmcnt(4)
	v_add_f32_e32 v149, v149, v200
	s_waitcnt lgkmcnt(3)
	v_add_f32_e32 v160, v160, v216
	s_waitcnt lgkmcnt(2)
	v_add_f32_e32 v161, v161, v220
	s_waitcnt lgkmcnt(1)
	v_add_f32_e32 v162, v162, v224
	s_waitcnt lgkmcnt(0)
	v_add_f32_e32 v163, v163, v228
	v_add_u32_e32 v240, 0x2000, v242
	s_and_saveexec_b64 s[22:23], s[42:43]
	global_store_dword v242, v146, s[8:9]
	global_store_dword v242, v147, s[8:9] offset:1024
	global_store_dword v242, v148, s[8:9] offset:2048
	global_store_dword v242, v149, s[8:9] offset:3072
	global_store_dword v240, v160, s[8:9]
	global_store_dword v240, v161, s[8:9] offset:1024
	global_store_dword v240, v162, s[8:9] offset:2048
	global_store_dword v240, v163, s[8:9] offset:3072
	s_or_b64 exec, exec, s[22:23]
	s_lshr_b32 s13, s13, 2
	s_lshl_b32 s13, s13, 6
	s_lshl_b32 s20, s38, 8
	s_add_i32 s13, s13, s20
	s_mov_b32 s53, s55
	s_mov_b32 s51, 0x800000
	s_mov_b64 s[48:49], 0x4000
	s_movk_i32 s55, 0xff00
	s_movk_i32 s54, 0x110
	s_andn2_b64 vcc, exec, s[44:45]
	s_mov_b64 s[20:21], -1
	s_cbranch_vccnz .LBB0_947
	s_andn2_b64 vcc, exec, s[0:1]
	s_cbranch_vccnz .LBB0_946
	s_barrier
	s_branch .LBB0_946

.LBB0_1117:
	v_and_b32_e32 v205, 63, v206
	v_lshrrev_b32_e32 v214, 6, v206
	v_and_b32_e32 v215, 15, v205
	v_readfirstlane_b32 s9, v214
	v_lshrrev_b32_e32 v178, 4, v205
	v_xor_b32_e32 v240, 16, v205
	v_xor_b32_e32 v241, 32, v205
	v_lshlrev_b32_e32 v240, 2, v240
	v_lshlrev_b32_e32 v241, 2, v241
	s_and_b32 s16, s9, 3
	s_mov_b32 s18, s16
	s_lshl_b32 s16, s16, 5
	s_lshl_b32 s17, s33, 8
	s_add_i32 s16, s16, s17
	v_lshl_add_u32 v179, v178, 3, s16
	s_lshl_b32 s17, s33, 2
	s_add_i32 s18, s18, s17
	s_lshl_b32 s18, s18, 2
	s_lshr_b32 s16, s9, 2
	s_lshl_b32 s16, s16, 6
	s_lshl_b32 s17, s38, 8
	s_add_i32 s16, s16, s17
	v_add_u32_e32 v174, s16, v215
	v_lshlrev_b32_e32 v183, 12, v174
	v_lshl_add_u32 v183, v179, 2, v183
	v_lshrrev_b32_e32 v184, 1, v183
	v_lshl_add_u32 v242, v174, 6, s18
	v_mov_b32_e32 v185, v183
	v_mov_b32_e32 v186, v184
	global_load_dwordx4 v[188:191], v185, s[68:69]
	global_load_dwordx4 v[192:195], v185, s[68:69] offset:16
	global_load_dwordx4 v[196:199], v185, s[68:69] offset:512
	global_load_dwordx4 v[200:203], v185, s[68:69] offset:528
	v_add_u32_e32 v187, 0x10000, v183
	v_add_u32_e32 v204, 0x8000, v184
	global_load_dwordx4 v[216:219], v187, s[68:69]
	global_load_dwordx4 v[220:223], v187, s[68:69] offset:16
	global_load_dwordx4 v[224:227], v187, s[68:69] offset:512
	global_load_dwordx4 v[228:231], v187, s[68:69] offset:528
	v_add_u32_e32 v243, 0x20000, v183
	v_add_u32_e32 v214, 0x10000, v184
	global_load_dwordx4 v[232:235], v243, s[68:69]
	global_load_dwordx4 v[236:239], v243, s[68:69] offset:16
	s_waitcnt vmcnt(8)
	v_pk_add_f32 v[132:133], v[132:133], v[188:189]
	v_pk_add_f32 v[134:135], v[134:135], v[190:191]
	v_pk_add_f32 v[128:129], v[128:129], v[192:193]
	v_pk_add_f32 v[130:131], v[130:131], v[194:195]
	global_load_dwordx4 v[188:191], v243, s[68:69] offset:512
	global_load_dwordx4 v[192:195], v243, s[68:69] offset:528
	global_store_dwordx4 v185, v[132:135], s[68:69]
	global_store_dwordx4 v185, v[128:131], s[68:69] offset:16
	v_cvt_pk_bf16_f32 v174, v132, v133
	v_cvt_pk_bf16_f32 v175, v134, v135
	v_cvt_pk_bf16_f32 v176, v128, v129
	v_cvt_pk_bf16_f32 v177, v130, v131
	global_store_dwordx4 v186, v[174:177], s[2:3]
	v_mul_f32_e32 v178, v133, v133
	v_fmac_f32_e32 v178, v132, v132
	v_mul_f32_e32 v179, v135, v135
	v_fmac_f32_e32 v179, v134, v134
	v_add_f32_e32 v178, v178, v179
	v_mul_f32_e32 v179, v129, v129
	v_fmac_f32_e32 v179, v128, v128
	v_add_f32_e32 v178, v178, v179
	v_mul_f32_e32 v179, v131, v131
	v_fmac_f32_e32 v179, v130, v130
	v_add_f32_e32 v146, v179, v178
	s_waitcnt vmcnt(11)
	v_pk_add_f32 v[124:125], v[124:125], v[196:197]
	v_pk_add_f32 v[126:127], v[126:127], v[198:199]
	v_pk_add_f32 v[120:121], v[120:121], v[200:201]
	v_pk_add_f32 v[122:123], v[122:123], v[202:203]
	v_add_u32_e32 v215, 0x30000, v183
	v_add_u32_e32 v205, 0x18000, v184
	global_load_dwordx4 v[196:199], v215, s[68:69]
	global_load_dwordx4 v[200:203], v215, s[68:69] offset:16
	global_store_dwordx4 v185, v[124:127], s[68:69] offset:512
	global_store_dwordx4 v185, v[120:123], s[68:69] offset:528
	v_cvt_pk_bf16_f32 v244, v124, v125
	v_cvt_pk_bf16_f32 v245, v126, v127
	v_cvt_pk_bf16_f32 v246, v120, v121
	v_cvt_pk_bf16_f32 v247, v122, v123
	global_store_dwordx4 v186, v[244:247], s[2:3] offset:256
	v_mul_f32_e32 v178, v125, v125
	v_fmac_f32_e32 v178, v124, v124
	v_mul_f32_e32 v179, v127, v127
	v_fmac_f32_e32 v179, v126, v126
	v_add_f32_e32 v178, v178, v179
	v_mul_f32_e32 v179, v121, v121
	v_fmac_f32_e32 v179, v120, v120
	v_add_f32_e32 v178, v178, v179
	v_mul_f32_e32 v179, v123, v123
	v_fmac_f32_e32 v179, v122, v122
	v_add_f32_e32 v178, v179, v178
	v_add_f32_e32 v146, v146, v178
	s_waitcnt vmcnt(14)
	v_pk_add_f32 v[116:117], v[116:117], v[216:217]
	v_pk_add_f32 v[118:119], v[118:119], v[218:219]
	v_pk_add_f32 v[112:113], v[112:113], v[220:221]
	v_pk_add_f32 v[114:115], v[114:115], v[222:223]
	global_load_dwordx4 v[216:219], v215, s[68:69] offset:512
	global_load_dwordx4 v[220:223], v215, s[68:69] offset:528
	global_store_dwordx4 v187, v[116:119], s[68:69]
	global_store_dwordx4 v187, v[112:115], s[68:69] offset:16
	v_cvt_pk_bf16_f32 v174, v116, v117
	v_cvt_pk_bf16_f32 v175, v118, v119
	v_cvt_pk_bf16_f32 v176, v112, v113
	v_cvt_pk_bf16_f32 v177, v114, v115
	global_store_dwordx4 v204, v[174:177], s[2:3]
	v_mul_f32_e32 v178, v117, v117
	v_fmac_f32_e32 v178, v116, v116
	v_mul_f32_e32 v179, v119, v119
	v_fmac_f32_e32 v179, v118, v118
	v_add_f32_e32 v178, v178, v179
	v_mul_f32_e32 v179, v113, v113
	v_fmac_f32_e32 v179, v112, v112
	v_add_f32_e32 v178, v178, v179
	v_mul_f32_e32 v179, v115, v115
	v_fmac_f32_e32 v179, v114, v114
	v_add_f32_e32 v147, v179, v178
	s_waitcnt vmcnt(17)
	v_pk_add_f32 v[108:109], v[108:109], v[224:225]
	v_pk_add_f32 v[110:111], v[110:111], v[226:227]
	v_pk_add_f32 v[104:105], v[104:105], v[228:229]
	v_pk_add_f32 v[106:107], v[106:107], v[230:231]
	v_add_u32_e32 v185, 0x80000, v183
	v_add_u32_e32 v186, 0x40000, v184
	global_load_dwordx4 v[224:227], v185, s[68:69]
	global_load_dwordx4 v[228:231], v185, s[68:69] offset:16
	global_store_dwordx4 v187, v[108:111], s[68:69] offset:512
	global_store_dwordx4 v187, v[104:107], s[68:69] offset:528
	v_cvt_pk_bf16_f32 v244, v108, v109
	v_cvt_pk_bf16_f32 v245, v110, v111
	v_cvt_pk_bf16_f32 v246, v104, v105
	v_cvt_pk_bf16_f32 v247, v106, v107
	global_store_dwordx4 v204, v[244:247], s[2:3] offset:256
	v_mul_f32_e32 v178, v109, v109
	v_fmac_f32_e32 v178, v108, v108
	v_mul_f32_e32 v179, v111, v111
	v_fmac_f32_e32 v179, v110, v110
	v_add_f32_e32 v178, v178, v179
	v_mul_f32_e32 v179, v105, v105
	v_fmac_f32_e32 v179, v104, v104
	v_add_f32_e32 v178, v178, v179
	v_mul_f32_e32 v179, v107, v107
	v_fmac_f32_e32 v179, v106, v106
	v_add_f32_e32 v178, v179, v178
	v_add_f32_e32 v147, v147, v178
	s_waitcnt vmcnt(20)
	v_pk_add_f32 v[100:101], v[100:101], v[232:233]
	v_pk_add_f32 v[102:103], v[102:103], v[234:235]
	v_pk_add_f32 v[96:97], v[96:97], v[236:237]
	v_pk_add_f32 v[98:99], v[98:99], v[238:239]
	global_load_dwordx4 v[232:235], v185, s[68:69] offset:512
	global_load_dwordx4 v[236:239], v185, s[68:69] offset:528
	global_store_dwordx4 v243, v[100:103], s[68:69]
	global_store_dwordx4 v243, v[96:99], s[68:69] offset:16
	v_cvt_pk_bf16_f32 v174, v100, v101
	v_cvt_pk_bf16_f32 v175, v102, v103
	v_cvt_pk_bf16_f32 v176, v96, v97
	v_cvt_pk_bf16_f32 v177, v98, v99
	global_store_dwordx4 v214, v[174:177], s[2:3]
	v_mul_f32_e32 v178, v101, v101
	v_fmac_f32_e32 v178, v100, v100
	v_mul_f32_e32 v179, v103, v103
	v_fmac_f32_e32 v179, v102, v102
	v_add_f32_e32 v178, v178, v179
	v_mul_f32_e32 v179, v97, v97
	v_fmac_f32_e32 v179, v96, v96
	v_add_f32_e32 v178, v178, v179
	v_mul_f32_e32 v179, v99, v99
	v_fmac_f32_e32 v179, v98, v98
	v_add_f32_e32 v148, v179, v178
	s_waitcnt vmcnt(23)
	v_pk_add_f32 v[92:93], v[92:93], v[188:189]
	v_pk_add_f32 v[94:95], v[94:95], v[190:191]
	v_pk_add_f32 v[88:89], v[88:89], v[192:193]
	v_pk_add_f32 v[90:91], v[90:91], v[194:195]
	v_add_u32_e32 v187, 0x90000, v183
	v_add_u32_e32 v204, 0x48000, v184
	global_load_dwordx4 v[188:191], v187, s[68:69]
	global_load_dwordx4 v[192:195], v187, s[68:69] offset:16
	global_store_dwordx4 v243, v[92:95], s[68:69] offset:512
	global_store_dwordx4 v243, v[88:91], s[68:69] offset:528
	v_cvt_pk_bf16_f32 v244, v92, v93
	v_cvt_pk_bf16_f32 v245, v94, v95
	v_cvt_pk_bf16_f32 v246, v88, v89
	v_cvt_pk_bf16_f32 v247, v90, v91
	global_store_dwordx4 v214, v[244:247], s[2:3] offset:256
	v_mul_f32_e32 v178, v93, v93
	v_fmac_f32_e32 v178, v92, v92
	v_mul_f32_e32 v179, v95, v95
	v_fmac_f32_e32 v179, v94, v94
	v_add_f32_e32 v178, v178, v179
	v_mul_f32_e32 v179, v89, v89
	v_fmac_f32_e32 v179, v88, v88
	v_add_f32_e32 v178, v178, v179
	v_mul_f32_e32 v179, v91, v91
	v_fmac_f32_e32 v179, v90, v90
	v_add_f32_e32 v178, v179, v178
	v_add_f32_e32 v148, v148, v178
	s_waitcnt vmcnt(23)
	v_pk_add_f32 v[84:85], v[84:85], v[196:197]
	v_pk_add_f32 v[86:87], v[86:87], v[198:199]
	v_pk_add_f32 v[80:81], v[80:81], v[200:201]
	v_pk_add_f32 v[82:83], v[82:83], v[202:203]
	global_load_dwordx4 v[196:199], v187, s[68:69] offset:512
	global_load_dwordx4 v[200:203], v187, s[68:69] offset:528
	global_store_dwordx4 v215, v[84:87], s[68:69]
	global_store_dwordx4 v215, v[80:83], s[68:69] offset:16
	v_cvt_pk_bf16_f32 v174, v84, v85
	v_cvt_pk_bf16_f32 v175, v86, v87
	v_cvt_pk_bf16_f32 v176, v80, v81
	v_cvt_pk_bf16_f32 v177, v82, v83
	global_store_dwordx4 v205, v[174:177], s[2:3]
	v_mul_f32_e32 v178, v85, v85
	v_fmac_f32_e32 v178, v84, v84
	v_mul_f32_e32 v179, v87, v87
	v_fmac_f32_e32 v179, v86, v86
	v_add_f32_e32 v178, v178, v179
	v_mul_f32_e32 v179, v81, v81
	v_fmac_f32_e32 v179, v80, v80
	v_add_f32_e32 v178, v178, v179
	v_mul_f32_e32 v179, v83, v83
	v_fmac_f32_e32 v179, v82, v82
	v_add_f32_e32 v149, v179, v178
	s_waitcnt vmcnt(23)
	v_pk_add_f32 v[76:77], v[76:77], v[216:217]
	v_pk_add_f32 v[78:79], v[78:79], v[218:219]
	v_pk_add_f32 v[72:73], v[72:73], v[220:221]
	v_pk_add_f32 v[74:75], v[74:75], v[222:223]
	v_add_u32_e32 v243, 0xa0000, v183
	v_add_u32_e32 v214, 0x50000, v184
	global_load_dwordx4 v[216:219], v243, s[68:69]
	global_load_dwordx4 v[220:223], v243, s[68:69] offset:16
	global_store_dwordx4 v215, v[76:79], s[68:69] offset:512
	global_store_dwordx4 v215, v[72:75], s[68:69] offset:528
	v_cvt_pk_bf16_f32 v244, v76, v77
	v_cvt_pk_bf16_f32 v245, v78, v79
	v_cvt_pk_bf16_f32 v246, v72, v73
	v_cvt_pk_bf16_f32 v247, v74, v75
	global_store_dwordx4 v205, v[244:247], s[2:3] offset:256
	v_mul_f32_e32 v178, v77, v77
	v_fmac_f32_e32 v178, v76, v76
	v_mul_f32_e32 v179, v79, v79
	v_fmac_f32_e32 v179, v78, v78
	v_add_f32_e32 v178, v178, v179
	v_mul_f32_e32 v179, v73, v73
	v_fmac_f32_e32 v179, v72, v72
	v_add_f32_e32 v178, v178, v179
	v_mul_f32_e32 v179, v75, v75
	v_fmac_f32_e32 v179, v74, v74
	v_add_f32_e32 v178, v179, v178
	v_add_f32_e32 v149, v149, v178
	s_waitcnt vmcnt(23)
	v_pk_add_f32 v[68:69], v[68:69], v[224:225]
	v_pk_add_f32 v[70:71], v[70:71], v[226:227]
	v_pk_add_f32 v[64:65], v[64:65], v[228:229]
	v_pk_add_f32 v[66:67], v[66:67], v[230:231]
	global_load_dwordx4 v[224:227], v243, s[68:69] offset:512
	global_load_dwordx4 v[228:231], v243, s[68:69] offset:528
	global_store_dwordx4 v185, v[68:71], s[68:69]
	global_store_dwordx4 v185, v[64:67], s[68:69] offset:16
	v_cvt_pk_bf16_f32 v174, v68, v69
	v_cvt_pk_bf16_f32 v175, v70, v71
	v_cvt_pk_bf16_f32 v176, v64, v65
	v_cvt_pk_bf16_f32 v177, v66, v67
	global_store_dwordx4 v186, v[174:177], s[2:3]
	v_mul_f32_e32 v178, v69, v69
	v_fmac_f32_e32 v178, v68, v68
	v_mul_f32_e32 v179, v71, v71
	v_fmac_f32_e32 v179, v70, v70
	v_add_f32_e32 v178, v178, v179
	v_mul_f32_e32 v179, v65, v65
	v_fmac_f32_e32 v179, v64, v64
	v_add_f32_e32 v178, v178, v179
	v_mul_f32_e32 v179, v67, v67
	v_fmac_f32_e32 v179, v66, v66
	v_add_f32_e32 v160, v179, v178
	s_waitcnt vmcnt(23)
	v_pk_add_f32 v[60:61], v[60:61], v[232:233]
	v_pk_add_f32 v[62:63], v[62:63], v[234:235]
	v_pk_add_f32 v[56:57], v[56:57], v[236:237]
	v_pk_add_f32 v[58:59], v[58:59], v[238:239]
	v_add_u32_e32 v215, 0xb0000, v183
	v_add_u32_e32 v205, 0x58000, v184
	global_load_dwordx4 v[232:235], v215, s[68:69]
	global_load_dwordx4 v[236:239], v215, s[68:69] offset:16
	global_store_dwordx4 v185, v[60:63], s[68:69] offset:512
	global_store_dwordx4 v185, v[56:59], s[68:69] offset:528
	v_cvt_pk_bf16_f32 v244, v60, v61
	v_cvt_pk_bf16_f32 v245, v62, v63
	v_cvt_pk_bf16_f32 v246, v56, v57
	v_cvt_pk_bf16_f32 v247, v58, v59
	global_store_dwordx4 v186, v[244:247], s[2:3] offset:256
	v_mul_f32_e32 v178, v61, v61
	v_fmac_f32_e32 v178, v60, v60
	v_mul_f32_e32 v179, v63, v63
	v_fmac_f32_e32 v179, v62, v62
	v_add_f32_e32 v178, v178, v179
	v_mul_f32_e32 v179, v57, v57
	v_fmac_f32_e32 v179, v56, v56
	v_add_f32_e32 v178, v178, v179
	v_mul_f32_e32 v179, v59, v59
	v_fmac_f32_e32 v179, v58, v58
	v_add_f32_e32 v178, v179, v178
	v_add_f32_e32 v160, v160, v178
	s_waitcnt vmcnt(23)
	v_pk_add_f32 v[52:53], v[52:53], v[188:189]
	v_pk_add_f32 v[54:55], v[54:55], v[190:191]
	v_pk_add_f32 v[48:49], v[48:49], v[192:193]
	v_pk_add_f32 v[50:51], v[50:51], v[194:195]
	global_load_dwordx4 v[188:191], v215, s[68:69] offset:512
	global_load_dwordx4 v[192:195], v215, s[68:69] offset:528
	global_store_dwordx4 v187, v[52:55], s[68:69]
	global_store_dwordx4 v187, v[48:51], s[68:69] offset:16
	v_cvt_pk_bf16_f32 v174, v52, v53
	v_cvt_pk_bf16_f32 v175, v54, v55
	v_cvt_pk_bf16_f32 v176, v48, v49
	v_cvt_pk_bf16_f32 v177, v50, v51
	global_store_dwordx4 v204, v[174:177], s[2:3]
	v_mul_f32_e32 v178, v53, v53
	v_fmac_f32_e32 v178, v52, v52
	v_mul_f32_e32 v179, v55, v55
	v_fmac_f32_e32 v179, v54, v54
	v_add_f32_e32 v178, v178, v179
	v_mul_f32_e32 v179, v49, v49
	v_fmac_f32_e32 v179, v48, v48
	v_add_f32_e32 v178, v178, v179
	v_mul_f32_e32 v179, v51, v51
	v_fmac_f32_e32 v179, v50, v50
	v_add_f32_e32 v161, v179, v178
	s_waitcnt vmcnt(23)
	v_pk_add_f32 v[44:45], v[44:45], v[196:197]
	v_pk_add_f32 v[46:47], v[46:47], v[198:199]
	v_pk_add_f32 v[40:41], v[40:41], v[200:201]
	v_pk_add_f32 v[42:43], v[42:43], v[202:203]
	global_store_dwordx4 v187, v[44:47], s[68:69] offset:512
	global_store_dwordx4 v187, v[40:43], s[68:69] offset:528
	v_cvt_pk_bf16_f32 v244, v44, v45
	v_cvt_pk_bf16_f32 v245, v46, v47
	v_cvt_pk_bf16_f32 v246, v40, v41
	v_cvt_pk_bf16_f32 v247, v42, v43
	global_store_dwordx4 v204, v[244:247], s[2:3] offset:256
	v_mul_f32_e32 v178, v45, v45
	v_fmac_f32_e32 v178, v44, v44
	v_mul_f32_e32 v179, v47, v47
	v_fmac_f32_e32 v179, v46, v46
	v_add_f32_e32 v178, v178, v179
	v_mul_f32_e32 v179, v41, v41
	v_fmac_f32_e32 v179, v40, v40
	v_add_f32_e32 v178, v178, v179
	v_mul_f32_e32 v179, v43, v43
	v_fmac_f32_e32 v179, v42, v42
	v_add_f32_e32 v178, v179, v178
	v_add_f32_e32 v161, v161, v178
	s_waitcnt vmcnt(21)
	v_pk_add_f32 v[36:37], v[36:37], v[216:217]
	v_pk_add_f32 v[38:39], v[38:39], v[218:219]
	v_pk_add_f32 v[32:33], v[32:33], v[220:221]
	v_pk_add_f32 v[34:35], v[34:35], v[222:223]
	global_store_dwordx4 v243, v[36:39], s[68:69]
	global_store_dwordx4 v243, v[32:35], s[68:69] offset:16
	v_cvt_pk_bf16_f32 v174, v36, v37
	v_cvt_pk_bf16_f32 v175, v38, v39
	v_cvt_pk_bf16_f32 v176, v32, v33
	v_cvt_pk_bf16_f32 v177, v34, v35
	global_store_dwordx4 v214, v[174:177], s[2:3]
	v_mul_f32_e32 v178, v37, v37
	v_fmac_f32_e32 v178, v36, v36
	v_mul_f32_e32 v179, v39, v39
	v_fmac_f32_e32 v179, v38, v38
	v_add_f32_e32 v178, v178, v179
	v_mul_f32_e32 v179, v33, v33
	v_fmac_f32_e32 v179, v32, v32
	v_add_f32_e32 v178, v178, v179
	v_mul_f32_e32 v179, v35, v35
	v_fmac_f32_e32 v179, v34, v34
	v_add_f32_e32 v162, v179, v178
	s_waitcnt vmcnt(19)
	v_pk_add_f32 v[28:29], v[28:29], v[224:225]
	v_pk_add_f32 v[30:31], v[30:31], v[226:227]
	v_pk_add_f32 v[24:25], v[24:25], v[228:229]
	v_pk_add_f32 v[26:27], v[26:27], v[230:231]
	global_store_dwordx4 v243, v[28:31], s[68:69] offset:512
	global_store_dwordx4 v243, v[24:27], s[68:69] offset:528
	v_cvt_pk_bf16_f32 v244, v28, v29
	v_cvt_pk_bf16_f32 v245, v30, v31
	v_cvt_pk_bf16_f32 v246, v24, v25
	v_cvt_pk_bf16_f32 v247, v26, v27
	global_store_dwordx4 v214, v[244:247], s[2:3] offset:256
	v_mul_f32_e32 v178, v29, v29
	v_fmac_f32_e32 v178, v28, v28
	v_mul_f32_e32 v179, v31, v31
	v_fmac_f32_e32 v179, v30, v30
	v_add_f32_e32 v178, v178, v179
	v_mul_f32_e32 v179, v25, v25
	v_fmac_f32_e32 v179, v24, v24
	v_add_f32_e32 v178, v178, v179
	v_mul_f32_e32 v179, v27, v27
	v_fmac_f32_e32 v179, v26, v26
	v_add_f32_e32 v178, v179, v178
	v_add_f32_e32 v162, v162, v178
	s_waitcnt vmcnt(17)
	v_pk_add_f32 v[20:21], v[20:21], v[232:233]
	v_pk_add_f32 v[22:23], v[22:23], v[234:235]
	v_pk_add_f32 v[16:17], v[16:17], v[236:237]
	v_pk_add_f32 v[18:19], v[18:19], v[238:239]
	global_store_dwordx4 v215, v[20:23], s[68:69]
	global_store_dwordx4 v215, v[16:19], s[68:69] offset:16
	v_cvt_pk_bf16_f32 v174, v20, v21
	v_cvt_pk_bf16_f32 v175, v22, v23
	v_cvt_pk_bf16_f32 v176, v16, v17
	v_cvt_pk_bf16_f32 v177, v18, v19
	global_store_dwordx4 v205, v[174:177], s[2:3]
	v_mul_f32_e32 v178, v21, v21
	v_fmac_f32_e32 v178, v20, v20
	v_mul_f32_e32 v179, v23, v23
	v_fmac_f32_e32 v179, v22, v22
	v_add_f32_e32 v178, v178, v179
	v_mul_f32_e32 v179, v17, v17
	v_fmac_f32_e32 v179, v16, v16
	v_add_f32_e32 v178, v178, v179
	v_mul_f32_e32 v179, v19, v19
	v_fmac_f32_e32 v179, v18, v18
	v_add_f32_e32 v163, v179, v178
	s_waitcnt vmcnt(15)
	v_pk_add_f32 v[12:13], v[12:13], v[188:189]
	v_pk_add_f32 v[14:15], v[14:15], v[190:191]
	v_pk_add_f32 v[8:9], v[8:9], v[192:193]
	v_pk_add_f32 v[10:11], v[10:11], v[194:195]
	global_store_dwordx4 v215, v[12:15], s[68:69] offset:512
	global_store_dwordx4 v215, v[8:11], s[68:69] offset:528
	v_cvt_pk_bf16_f32 v244, v12, v13
	v_cvt_pk_bf16_f32 v245, v14, v15
	v_cvt_pk_bf16_f32 v246, v8, v9
	v_cvt_pk_bf16_f32 v247, v10, v11
	global_store_dwordx4 v205, v[244:247], s[2:3] offset:256
	v_mul_f32_e32 v178, v13, v13
	v_fmac_f32_e32 v178, v12, v12
	v_mul_f32_e32 v179, v15, v15
	v_fmac_f32_e32 v179, v14, v14
	v_add_f32_e32 v178, v178, v179
	v_mul_f32_e32 v179, v9, v9
	v_fmac_f32_e32 v179, v8, v8
	v_add_f32_e32 v178, v178, v179
	v_mul_f32_e32 v179, v11, v11
	v_fmac_f32_e32 v179, v10, v10
	v_add_f32_e32 v178, v179, v178
	v_add_f32_e32 v163, v163, v178
	ds_bpermute_b32 v188, v240, v146
	ds_bpermute_b32 v192, v240, v147
	ds_bpermute_b32 v196, v240, v148
	ds_bpermute_b32 v200, v240, v149
	ds_bpermute_b32 v216, v240, v160
	ds_bpermute_b32 v220, v240, v161
	ds_bpermute_b32 v224, v240, v162
	ds_bpermute_b32 v228, v240, v163
	s_waitcnt lgkmcnt(7)
	v_add_f32_e32 v146, v146, v188
	s_waitcnt lgkmcnt(6)
	v_add_f32_e32 v147, v147, v192
	s_waitcnt lgkmcnt(5)
	v_add_f32_e32 v148, v148, v196
	s_waitcnt lgkmcnt(4)
	v_add_f32_e32 v149, v149, v200
	s_waitcnt lgkmcnt(3)
	v_add_f32_e32 v160, v160, v216
	s_waitcnt lgkmcnt(2)
	v_add_f32_e32 v161, v161, v220
	s_waitcnt lgkmcnt(1)
	v_add_f32_e32 v162, v162, v224
	s_waitcnt lgkmcnt(0)
	v_add_f32_e32 v163, v163, v228
	ds_bpermute_b32 v188, v241, v146
	ds_bpermute_b32 v192, v241, v147
	ds_bpermute_b32 v196, v241, v148
	ds_bpermute_b32 v200, v241, v149
	ds_bpermute_b32 v216, v241, v160
	ds_bpermute_b32 v220, v241, v161
	ds_bpermute_b32 v224, v241, v162
	ds_bpermute_b32 v228, v241, v163
	s_waitcnt lgkmcnt(7)
	v_add_f32_e32 v146, v146, v188
	s_waitcnt lgkmcnt(6)
	v_add_f32_e32 v147, v147, v192
	s_waitcnt lgkmcnt(5)
	v_add_f32_e32 v148, v148, v196
	s_waitcnt lgkmcnt(4)
	v_add_f32_e32 v149, v149, v200
	s_waitcnt lgkmcnt(3)
	v_add_f32_e32 v160, v160, v216
	s_waitcnt lgkmcnt(2)
	v_add_f32_e32 v161, v161, v220
	s_waitcnt lgkmcnt(1)
	v_add_f32_e32 v162, v162, v224
	s_waitcnt lgkmcnt(0)
	v_add_f32_e32 v163, v163, v228
	v_add_u32_e32 v240, 0x2000, v242
	s_and_saveexec_b64 s[18:19], s[40:41]
	global_store_dword v242, v146, s[4:5]
	global_store_dword v242, v147, s[4:5] offset:1024
	global_store_dword v242, v148, s[4:5] offset:2048
	global_store_dword v242, v149, s[4:5] offset:3072
	global_store_dword v240, v160, s[4:5]
	global_store_dword v240, v161, s[4:5] offset:1024
	global_store_dword v240, v162, s[4:5] offset:2048
	global_store_dword v240, v163, s[4:5] offset:3072
	s_or_b64 exec, exec, s[18:19]
	s_lshr_b32 s9, s9, 2
	s_lshl_b32 s9, s9, 6
	s_lshl_b32 s16, s38, 8
	s_add_i32 s9, s9, s16
	s_mov_b64 s[46:47], 0x8000
	s_mov_b64 s[48:49], 0x4000
	s_andn2_b64 vcc, exec, s[42:43]
	s_mov_b64 s[16:17], -1
	s_cbranch_vccnz .LBB0_1106
	s_andn2_b64 vcc, exec, s[0:1]
	s_cbranch_vccnz .LBB0_1105
	s_barrier
	s_branch .LBB0_1105
